# v17 + swapped-GEMM (V^T / Fourier feature) unit assignment rotated by 96 / 144 workgroups so the extra units of in-proj, part 0 and part 1 fall on different workgroups
# speedup vs baseline: 1.0033x; 1.0033x over previous
;     DI bool next(int i, Unit& u) const {
;         const long L = (long)i * G + c; if (L >= nwg) return false;
;         if (fmode) { const int w = (int)L; u.pz = 0;
;             if (w < 272) { const int b = w / 17, r = w % 17; if (r < 9) { u.pm = 3; u.pn = b * 16 + r; } else { u.pm = 4; u.pn = b * 16 + r - 1; } }
;             else { const int cq = w - 272; u.pm = 3 + (cq & 1); u.pn = TL / 256 + (cq >> 1); }
;             return true; }
;         int wgid = (int)L; { const int q = nwg / NXCD, r = nwg % NXCD, xcd = wgid % NXCD, off = wgid / NXCD; wgid = (xcd < r ? xcd * (q + 1) : r * (q + 1) + (xcd - r) * q) + off; }
;         u.pz = wgid / per; const int w = wgid % per;
;         const int nig = WGM * nN, gid = w / nig, fm = gid * WGM, gsz = (nM - fm) < WGM ? (nM - fm) : WGM;
;         u.pm = pm0 + fm + ((w % nig) % gsz); u.pn = (w % nig) / gsz; return true;
; template <class Epi>
; DI void gemm_phase(LAS unsigned char* lds, int tid, const Gemm g, const Order& S, const Epi& E) {
;     ...
;     for (int i = 0; i < 2; ++i) { int R, C; stage_rc(tid * 16 + i * 8192, R, C); const int Rb = (R & ~31) + perm32(R & 31);
;         voffA[i] = (unsigned)(R * g.lda + C) * 2u; voffB[i] = (unsigned)(Rb * g.ldb + C) * 2u; }
;     const size_t kstep = (size_t)(BK * 2);
;     const size_t hstepA = (size_t)HALF * g.lda * 2, hstepB = (size_t)HALF * g.ldb * 2;
;     const unsigned ldsw = (unsigned)wid * 1024u;
;     const int aoff = lds_byte(wr * 64 + fr, fq * 8), boff = lds_byte(wc * 32 + fr, fq * 8);
.LBB0_367:
	s_and_b64 vcc, exec, s[4:5]
	s_cbranch_vccz .LBB0_440
	v_bfe_i32 v4, v164, 27, 1
	v_lshlrev_b32_e32 v0, 4, v164
	v_lshrrev_b32_e32 v4, 22, v4
	v_add_u32_e32 v4, v0, v4
	v_and_b32_e32 v4, 0xfffffc00, v4
	v_sub_u32_e32 v4, v0, v4
	v_lshrrev_b32_e32 v5, 4, v4
	s_add_u32 s10, s60, 0x32900000
	v_bitop3_b32 v4, v5, v4, 32 bitop3:0x6c
	s_addc_u32 s11, s61, 0
	v_ashrrev_i32_e32 v6, 31, v4
	s_add_u32 s16, s60, 0x36900000
	s_waitcnt lgkmcnt(0)
	v_ashrrev_i32_e32 v2, 31, v164
	v_lshrrev_b32_e32 v6, 26, v6
	s_addc_u32 s17, s61, 0
	v_readlane_b32 s4, v255, 7
	v_lshrrev_b32_e32 v2, 26, v2
	v_add_u32_e32 v6, v4, v6
	s_add_u32 s18, s60, 0x2c300000
	v_readlane_b32 s5, v255, 8
	v_add_u32_e32 v2, v164, v2
	v_ashrrev_i32_e32 v7, 6, v6
	v_and_b32_e32 v6, 0xc0, v6
	s_addc_u32 s19, s61, 0
	s_lshl_b64 s[4:5], s[4:5], 1
	v_ashrrev_i32_e32 v3, 6, v2
	v_sub_u32_e32 v4, v4, v6
	s_add_u32 s4, s60, s4
	v_lshlrev_b32_e32 v5, 3, v3
	v_lshlrev_b32_e32 v8, 5, v3
	v_ashrrev_i16_sdwa v4, v193, sext(v4) dst_sel:DWORD dst_unused:UNUSED_PAD src0_sel:DWORD src1_sel:BYTE_0
	s_addc_u32 s5, s61, s5
	v_and_b32_e32 v5, -16, v5
	v_and_b32_e32 v8, 32, v8
	v_bfe_i32 v4, v4, 0, 16
	s_add_u32 s28, s4, 0xa200000
	v_add_u32_e32 v5, v7, v5
	v_and_b32_e32 v10, 3, v7
	s_mov_b32 s4, 0x1fffe0
	v_add_lshl_u32 v8, v8, v4, 1
	v_add_u32_e32 v0, 0x2000, v0
	v_lshlrev_b32_e32 v6, 1, v5
	v_lshrrev_b32_e32 v9, 2, v5
	v_and_or_b32 v10, v5, s4, v10
	v_lshl_add_u32 v130, v5, 11, v8
	v_ashrrev_i32_e32 v5, 31, v0
	v_lshrrev_b32_e32 v5, 22, v5
	v_and_b32_e32 v6, 24, v6
	v_and_b32_e32 v9, 4, v9
	v_add_u32_e32 v5, v0, v5
	v_or3_b32 v6, v10, v9, v6
	v_ashrrev_i32_e32 v5, 10, v5
	v_lshl_add_u32 v132, v6, 11, v8
	v_mul_i32_i24_e32 v6, 0x400, v5
	v_sub_u32_e32 v0, v0, v6
	v_lshrrev_b32_e32 v6, 4, v0
	v_bitop3_b32 v0, v6, v0, 32 bitop3:0x6c
	v_ashrrev_i32_e32 v8, 31, v0
	v_lshrrev_b32_e32 v8, 26, v8
	v_lshlrev_b32_e32 v6, 3, v5
	v_add_u32_e32 v8, v0, v8
	s_addc_u32 s36, s5, 0
	v_and_b32_e32 v6, -16, v6
	v_ashrrev_i32_e32 v9, 6, v8
	s_add_u32 s37, s60, 0x36d00000
	v_add_u32_e32 v6, v9, v6
	v_and_b32_e32 v12, 3, v9
	s_addc_u32 s39, s61, 0
	v_and_or_b32 v12, v6, s4, v12
	s_mov_b32 s99, s2
	s_mov_b32 s101, s2
	s_cmp_eq_u32 s3, 0x100
	s_cbranch_scc0 .Lft_norot
	s_sub_u32 s99, s2, 96
	s_and_b32 s99, s99, 0xff
	s_sub_u32 s101, s2, 144
	s_and_b32 s101, s101, 0xff
.Lft_norot:
	s_mov_b32 s2, s101
	s_add_i32 s4, s2, 0xfffffef0
	s_lshr_b32 s4, s4, 1
	s_add_i32 s8, s4, 0x100
	s_mul_hi_i32 s4, s2, 0x78787879
	s_lshr_b32 s5, s4, 31
	s_ashr_i32 s4, s4, 3
	s_add_i32 s4, s4, s5
	s_mul_i32 s5, s4, 17
	s_sub_i32 s5, s2, s5
	s_lshl_b32 s4, s4, 4
	s_add_i32 s78, s78, 3
	s_add_i32 s9, s4, s5
	s_cmp_gt_i32 s5, 8
	s_cselect_b64 s[4:5], -1, 0
	s_and_b64 s[6:7], s[4:5], exec
	s_cselect_b32 s6, 4, 3
	s_cmp_lg_u64 s[4:5], 0
	s_subb_u32 s4, s9, 0
	s_cmpk_lt_i32 s2, 0x110
	s_cselect_b32 s46, s4, s8
	s_cselect_b32 s49, s6, s78
	s_mov_b32 s2, s99
	s_ashr_i32 s42, s2, 31
	s_lshr_b32 s5, s42, 29
	s_add_i32 s5, s2, s5
	s_ashr_i32 s7, s5, 3
	s_and_b32 s5, s5, -8
	s_sub_i32 s5, s2, s5
	s_ashr_i32 s43, s3, 31
	s_cmp_lt_i32 s5, 0
	s_movk_i32 s4, 0x67
	s_cselect_b32 s4, s4, 0x66
	s_mul_i32 s4, s4, s5
	s_add_i32 s4, s4, s7
	s_mul_hi_i32 s5, s4, 0xa0a0a0a1
	s_add_i32 s5, s5, s4
	s_lshr_b32 s6, s5, 31
	s_ashr_i32 s5, s5, 9
	s_add_i32 s5, s5, s6
	v_and_b32_e32 v8, 0xc0, v8
	s_mulk_i32 s5, 0x330
	v_lshlrev_b32_e32 v3, 14, v3
	v_sub_u32_e32 v0, v0, v8
	s_sub_i32 s4, s4, s5
	v_and_b32_e32 v3, 0xffff8000, v3
	v_lshlrev_b32_e32 v10, 5, v5
	v_ashrrev_i16_sdwa v0, v193, sext(v0) dst_sel:DWORD dst_unused:UNUSED_PAD src0_sel:DWORD src1_sel:BYTE_0
	s_sext_i32_i16 s5, s4
	v_lshl_add_u32 v3, v7, 11, v3
	v_and_b32_e32 v10, 32, v10
	v_bfe_i32 v0, v0, 0, 16
	v_lshlrev_b32_e32 v8, 1, v6
	v_lshrrev_b32_e32 v11, 2, v6
	s_mulk_i32 s5, 0x5556
	v_and_or_b32 v2, v2, 64, v3
	v_and_b32_e32 v8, 24, v8
	v_and_b32_e32 v11, 4, v11
	v_add_lshl_u32 v10, v10, v0, 1
	s_lshr_b32 s6, s5, 31
	s_lshr_b32 s5, s5, 16
	v_lshl_add_u32 v138, v4, 1, v2
	v_lshlrev_b32_e32 v2, 14, v5
	v_or3_b32 v8, v12, v11, v8
	v_lshl_add_u32 v134, v6, 11, v10
	v_lshrrev_b32_e32 v6, 1, v164
	s_add_i32 s5, s5, s6
	v_and_b32_e32 v2, 0xffff8000, v2
	v_lshl_add_u32 v136, v8, 11, v10
	v_and_b32_e32 v145, 15, v164
	v_and_b32_e32 v165, 24, v6
	v_lshlrev_b32_e32 v8, 2, v164
	s_mul_i32 s6, s5, 3
	v_lshl_add_u32 v2, v9, 11, v2
	v_lshlrev_b32_e32 v3, 6, v5
	v_lshlrev_b32_e32 v168, 1, v165
	v_lshlrev_b32_e32 v6, 6, v145
	v_and_b32_e32 v8, 32, v8
	s_sub_i32 s4, s4, s6
	v_and_or_b32 v2, v3, 64, v2
	s_mov_b32 s14, s26
	v_bitop3_b32 v170, v168, v8, v6 bitop3:0x36
	v_mov_b32_e32 v133, v1
	v_mov_b32_e32 v137, v1
	v_mov_b32_e32 v131, v1
	v_mov_b32_e32 v135, v1
	s_sext_i32_i16 s26, s4
	s_sext_i32_i16 s30, s5
	v_mov_b32_e32 v139, v1
	v_lshl_add_u32 v140, v0, 1, v2
	v_mov_b32_e32 v141, v1
	s_mov_b64 s[4:5], -1
	s_branch .LBB0_371

; DI const char* a_of(const Gemm& g, const Unit& u) { return (const char*)(g.A + (size_t)u.pz * g.zA + (size_t)u.pm * BM * g.lda); }
; DI const char* b_of(const Gemm& g, const Unit& u) { return (const char*)(g.Bt + (size_t)u.pz * g.zB + (size_t)u.pn * BM * g.ldb); }
; #define PG8_STAGE(bufoff, gbase, voff) do { _Pragma("unroll") for (int _i = 0; _i < 2; ++_i) \
;         __builtin_amdgcn_global_load_lds((const unsigned*)((const char*)(gbase) + (voff)[_i]), (LAS unsigned*)(lds + (bufoff) + ldsw + _i * 8192), 16, 0, 0); } while (0)
; #define PG8_WAIT_V(n) asm volatile("s_waitcnt vmcnt(" #n ")" ::: "memory")
; #define PG8_BAR __builtin_amdgcn_s_barrier()
; template <class Epi>
; DI void gemm_phase(LAS unsigned char* lds, int tid, const Gemm g, const Order& S, const Epi& E) {
;     ...
;     Unit cur, nxt; int ui = 0;
;     if (!S.next(0, cur)) return;
;     f32x4 acc[2][2][4][2];
; #pragma unroll
;     for (int a = 0; a < 2; ++a)
; #pragma unroll
;         for (int b = 0; b < 2; ++b)
; #pragma unroll
;             for (int m = 0; m < 4; ++m)
; #pragma unroll
;                 for (int n = 0; n < 2; ++n) acc[a][b][m][n] = (f32x4){0.f, 0.f, 0.f, 0.f};
;     bf16x8 At[4][2], B0[2][2], B1[2][2];
;     const char* cA = a_of(g, cur); const char* cB = b_of(g, cur);
;     PG8_STAGE(PG8_SB(0, 0), cB, voffB); PG8_STAGE(PG8_SB(0, 1), cB + hstepB, voffB); PG8_STAGE(PG8_SA(0, 0), cA, voffA); PG8_STAGE(PG8_SA(0, 1), cA + hstepA, voffA);
;     if (wr == 1) PG8_BAR;
;     PG8_WAIT_V(2); PG8_BAR;
;     PG8_STAGE(PG8_SB(1, 0), cB + kstep, voffB); PG8_STAGE(PG8_SA(1, 0), cA + kstep, voffA); PG8_STAGE(PG8_SB(1, 1), cB + hstepB + kstep, voffB);
.LBB0_371:
	s_xor_b64 s[68:69], s[4:5], -1
	s_and_b64 s[6:7], s[4:5], exec
	s_movk_i32 s6, 0x130
	s_cselect_b32 s70, 0x330, s6
	s_cselect_b32 s2, s99, s101
	s_cmp_lt_i32 s2, s70
	v_readfirstlane_b32 s20, v164
	s_cselect_b64 s[6:7], -1, 0
	s_cmp_ge_i32 s2, s70
	s_barrier
	s_cbranch_scc1 .LBB0_370
	s_and_b64 s[8:9], s[4:5], exec
	s_cselect_b32 s31, s59, s39
	s_cselect_b32 s51, s58, s37
	s_ashr_i32 s40, s20, 6
	s_ashr_i32 s33, s20, 8
	s_lshl_b32 s97, s40, 10
	s_and_b64 s[4:5], s[6:7], s[4:5]
	s_and_b64 s[4:5], s[4:5], exec
	s_cselect_b32 s80, s30, s46
	s_cselect_b32 s82, s26, s49
	s_ashr_i32 s83, s82, 31
	s_ashr_i32 s81, s80, 31
	s_lshl_b64 s[4:5], s[82:83], 19
	s_lshl_b64 s[6:7], s[80:81], 19
	s_add_u32 s88, s51, s6
	s_addc_u32 s89, s31, s7
	s_add_i32 s83, s97, 0
	s_add_i32 m0, s83, 0x10000
	v_lshl_add_u64 v[2:3], s[88:89], 0, v[132:133]
	global_load_lds_dwordx4 v[2:3], off
	s_add_i32 m0, s83, 0x12000
	s_add_u32 s6, s88, 0x40000
	v_lshl_add_u64 v[4:5], s[88:89], 0, v[136:137]
	s_addc_u32 s7, s89, 0
	global_load_lds_dwordx4 v[4:5], off
	s_add_i32 m0, s83, 0x14000
	v_lshl_add_u64 v[6:7], s[6:7], 0, v[132:133]
	global_load_lds_dwordx4 v[6:7], off
	s_add_i32 m0, s83, 0x16000
	s_add_u32 s8, s28, s4
	v_lshl_add_u64 v[6:7], s[6:7], 0, v[136:137]
	s_addc_u32 s9, s36, s5
	s_add_i32 s45, s83, 0x2000
	global_load_lds_dwordx4 v[6:7], off
	v_lshl_add_u64 v[8:9], s[8:9], 0, v[130:131]
	s_mov_b32 m0, s83
	s_add_u32 s4, s8, 0x40000
	global_load_lds_dwordx4 v[8:9], off
	v_lshl_add_u64 v[6:7], s[8:9], 0, v[134:135]
	s_mov_b32 m0, s45
	s_addc_u32 s5, s9, 0
	s_add_i32 s34, s83, 0x4000
	global_load_lds_dwordx4 v[6:7], off
	v_lshl_add_u64 v[10:11], s[4:5], 0, v[130:131]
	s_mov_b32 m0, s34
	s_add_i32 s22, s83, 0x6000
	global_load_lds_dwordx4 v[10:11], off
	v_lshl_add_u64 v[10:11], s[4:5], 0, v[134:135]
	s_mov_b32 m0, s22
	s_cmp_eq_u32 s33, 1
	global_load_lds_dwordx4 v[10:11], off
	s_cselect_b64 s[72:73], -1, 0
	s_cmp_lg_u32 s33, 1
	s_cbranch_scc1 .LBB0_374
	s_barrier

; DI const float* in_ptr(const Args& AR, int i) { asm volatile("" : "+s"(i)); return GLOBAL_PTR(const float, AR.in[i]); }
; __global__ void __launch_bounds__(512, 2) fwd_megakernel(Args args) {
;     ...
;             } else if (type == T_FT) {
;                 pg8::EpiFT E{WSP(bf16_t, WS_FT), WSP(bf16_t, WS_FTC), WSP(bf16_t, WS_VT)};
; #pragma unroll 1
;                 for (int part = 0; part < 2; ++part) {
;                     pg8::Gemm g{WSP(bf16_t, WS_WINAB) + (size_t)li * 2816 * DM + (size_t)1536 * DM, part ? WSP(bf16_t, WS_HS) : H, DM, DM, DM, 0, 0};
;                     pg8::Order S; if (part) S.init_fourier(F.G, bx); else S.init(3, TT / 256, 1, F.G, bx, 0);
;                     if (PM & 64) pg8::gemm_phase(F.lds, F.tid, g, S, E);
;                 }
;             } else if (type == T_POST) {
;                 if (PM & 128) postpass(F, even, even ? in_ptr(AR, 11) + li * 128 : in_ptr(AR, 15) + li * 128);
.LBB0_439:
	v_readlane_b32 s2, v255, 0
	s_load_dword s13, s[0:1], 0xa8
	v_readlane_b32 s36, v255, 11
	v_readlane_b32 s37, v255, 12
	v_readlane_b32 s22, v255, 25
	s_mov_b32 s26, s14
